# final RMSNorm row loop software-pipelined (next row loads in flight during the current row); on top of v43
# speedup vs baseline: 1.0171x; 1.0028x over previous
; __device__ __forceinline__ float bflo(unsigned w) { return __uint_as_float(w << 16); }
; __device__ __forceinline__ float bfhi(unsigned w) { return __uint_as_float(w & 0xffff0000u); }
; __global__ void __launch_bounds__(NWAVES * 64, 2) fwd_kernel(Args a_param) {
;     ...
;     if (((ENMASK >> 16) & 1) && IN(31)) {
;         const int layer = 1; PHASE_BEGIN();
;         f32x4 gq[8];
;         { const f32x4* gp = (const f32x4*)a.final_norm_g + lane;
; #pragma unroll
;           for (int j = 0; j < 8; ++j) gq[j] = gp[64 * j]; }
;         for (int m = gw; m < ML; m += ngw) {
;             const u32x2* hr = (const u32x2*)(U + (size_t)(MC + m) * DM) + lane; f32x4* xr = (f32x4*)(a.out + (size_t)m * DM) + lane;
;             f32x4 x[8]; float ss = 0.f;
; #pragma unroll
;             for (int j = 0; j < 8; ++j) { const u32x2 w = hr[64 * j]; x[j] = (f32x4){bflo(w.x), bfhi(w.x), bflo(w.y), bfhi(w.y)}; ss += (x[j].x * x[j].x + x[j].y * x[j].y) + (x[j].z * x[j].z + x[j].w * x[j].w); }
;             const float rstd = 1.0f / sqrtf(wave_sum(ss) * (1.0f / DM) + EPS);
.LBB0_1858:
	s_cmp_lt_i32 s90, 32
	s_cselect_b64 s[0:1], -1, 0
	s_cmp_gt_i32 s91, 31
	s_cselect_b64 s[2:3], -1, 0
	s_and_b64 s[0:1], s[0:1], s[2:3]
	s_and_b64 vcc, exec, s[0:1]
	s_cbranch_vccz .LBB0_1862
	v_readlane_b32 s1, v252, 2
	v_readfirstlane_b32 s0, v0
	s_ashr_i32 s0, s0, 6
	s_add_i32 s8, s0, s1
	s_cmpk_gt_i32 s8, 0x7fff
	s_cbranch_scc1 .LBB0_1862
	s_load_dwordx4 s[4:7], s[92:93], 0xc0
	s_load_dwordx2 s[10:11], s[92:93], 0xd0
	v_and_b32_e32 v36, 63, v0
	v_mov_b32_e32 v35, 0
	v_lshlrev_b32_e32 v34, 4, v36
	s_waitcnt lgkmcnt(0)
	v_lshl_add_u64 v[16:17], s[4:5], 0, v[34:35]
	s_waitcnt vmcnt(2)
	v_add_co_u32_e32 v32, vcc, 0x1000, v16
	global_load_dwordx4 v[0:3], v34, s[4:5]
	global_load_dwordx4 v[4:7], v34, s[4:5] offset:1024
	global_load_dwordx4 v[8:11], v34, s[4:5] offset:2048
	global_load_dwordx4 v[12:15], v34, s[4:5] offset:3072
	v_addc_co_u32_e32 v33, vcc, 0, v17, vcc
	global_load_dwordx4 v[16:19], v[32:33], off
	global_load_dwordx4 v[20:23], v[32:33], off offset:1024
	global_load_dwordx4 v[24:27], v[32:33], off offset:2048
	global_load_dwordx4 v[28:31], v[32:33], off offset:3072
	v_cmp_lt_i32_e32 vcc, v235, v232
	s_load_dword s1, s[88:89], 0x0
	v_readlane_b32 s4, v252, 2
	v_cndmask_b32_e32 v32, v230, v235, vcc
	v_cmp_lt_i32_e32 vcc, v234, v232
	v_lshlrev_b32_e32 v44, 2, v32
	s_waitcnt lgkmcnt(0)
	s_lshl_b32 s2, s1, 3
	v_cndmask_b32_e32 v32, v230, v234, vcc
	v_cmp_lt_i32_e32 vcc, v233, v232
	v_lshlrev_b32_e32 v45, 2, v32
	s_ashr_i32 s1, s4, 31
	v_cndmask_b32_e32 v32, v230, v233, vcc
	v_lshlrev_b32_e32 v46, 2, v32
	v_xor_b32_e32 v32, 8, v230
	v_cmp_lt_i32_e32 vcc, v32, v232
	s_ashr_i32 s3, s0, 31
	s_add_u32 s0, s4, s0
	v_cndmask_b32_e32 v32, v230, v32, vcc
	v_lshlrev_b32_e32 v47, 2, v32
	v_xor_b32_e32 v32, 16, v230
	v_cmp_lt_i32_e32 vcc, v32, v232
	s_addc_u32 s1, s1, s3
	s_lshl_b64 s[0:1], s[0:1], 13
	v_cndmask_b32_e32 v32, v230, v32, vcc
	v_lshlrev_b32_e32 v48, 2, v32
	v_xor_b32_e32 v32, 32, v230
	v_cmp_lt_i32_e32 vcc, v32, v232
	s_add_u32 s0, s6, s0
	s_addc_u32 s1, s7, s1
	v_cndmask_b32_e32 v32, v230, v32, vcc
	v_lshlrev_b32_e32 v49, 2, v32
	v_lshl_add_u64 v[32:33], s[0:1], 0, v[34:35]
	s_mov_b64 s[0:1], 0x1000
	v_lshl_add_u64 v[32:33], v[32:33], 0, s[0:1]
	s_add_i32 s0, s8, 0x400
	s_ashr_i32 s3, s2, 31
	s_ashr_i32 s1, s0, 31
	s_lshl_b64 s[4:5], s[2:3], 13
	s_lshl_b64 s[0:1], s[0:1], 12
	s_add_u32 s0, s10, s0
	v_lshlrev_b32_e32 v34, 3, v36
	s_addc_u32 s1, s11, s1
	v_lshl_add_u64 v[34:35], s[0:1], 0, v[34:35]
	s_mov_b64 s[0:1], 0x1a500000
	v_lshl_add_u64 v[34:35], v[34:35], 0, s[0:1]
	s_lshl_b64 s[6:7], s[2:3], 12
	v_mov_b32_e32 v50, 0x358637bd
	s_mov_b32 s3, 0xf800000
	v_mov_b32_e32 v51, 0x260
	global_load_dwordx2 v[110:111], v[34:35], off
	global_load_dwordx2 v[112:113], v[34:35], off offset:512
	global_load_dwordx2 v[114:115], v[34:35], off offset:1024
	global_load_dwordx2 v[116:117], v[34:35], off offset:1536
	global_load_dwordx2 v[118:119], v[34:35], off offset:2048
	global_load_dwordx2 v[120:121], v[34:35], off offset:2560
	global_load_dwordx2 v[122:123], v[34:35], off offset:3072
	global_load_dwordx2 v[124:125], v[34:35], off offset:3584
	v_lshl_add_u64 v[34:35], v[34:35], 0, s[6:7]
	s_waitcnt vmcnt(0)
.LBB0_1861:
	s_waitcnt vmcnt(8)
	v_mov_b64_e32 v[36:37], v[110:111]
	v_mov_b64_e32 v[38:39], v[112:113]
	v_mov_b64_e32 v[40:41], v[114:115]
	v_mov_b64_e32 v[42:43], v[116:117]
	v_mov_b64_e32 v[52:53], v[118:119]
	v_mov_b64_e32 v[54:55], v[120:121]
	v_mov_b64_e32 v[56:57], v[122:123]
	v_mov_b64_e32 v[58:59], v[124:125]
	global_load_dwordx2 v[110:111], v[34:35], off
	global_load_dwordx2 v[112:113], v[34:35], off offset:512
	global_load_dwordx2 v[114:115], v[34:35], off offset:1024
	global_load_dwordx2 v[116:117], v[34:35], off offset:1536
	global_load_dwordx2 v[118:119], v[34:35], off offset:2048
	global_load_dwordx2 v[120:121], v[34:35], off offset:2560
	global_load_dwordx2 v[122:123], v[34:35], off offset:3072
	global_load_dwordx2 v[124:125], v[34:35], off offset:3584
	s_add_i32 s8, s8, s2
	v_lshl_add_u64 v[34:35], v[34:35], 0, s[6:7]
	s_cmp_lt_i32 s8, 0x8000
	v_lshlrev_b32_e32 v60, 16, v36
	v_and_b32_e32 v61, 0xffff0000, v36
	v_lshlrev_b32_e32 v36, 16, v37
	v_and_b32_e32 v37, 0xffff0000, v37
	v_lshlrev_b32_e32 v63, 16, v39
	v_lshlrev_b32_e32 v62, 16, v38
	v_and_b32_e32 v39, 0xffff0000, v39
	v_and_b32_e32 v38, 0xffff0000, v38
	v_and_b32_e32 v65, 0xffff0000, v40
	v_lshlrev_b32_e32 v67, 16, v42
	v_lshlrev_b32_e32 v77, 16, v58
	v_mul_f32_e32 v66, v37, v37
	v_pk_mul_f32 v[80:81], v[38:39], v[38:39]
	v_mul_f32_e32 v76, v61, v61
	v_lshlrev_b32_e32 v64, 16, v40
	v_lshlrev_b32_e32 v40, 16, v41
	v_and_b32_e32 v41, 0xffff0000, v41
	v_mov_b32_e32 v83, v67
	v_mul_f32_e32 v82, v65, v65
	v_mov_b32_e32 v94, v62
	v_mov_b32_e32 v95, v38
	v_mov_b32_e32 v38, v63
	v_pk_fma_f32 v[100:101], v[36:37], v[36:37], v[66:67] op_sel_hi:[1,1,0]
	v_pk_fma_f32 v[62:63], v[62:63], v[62:63], v[80:81]
	v_pk_fma_f32 v[80:81], v[60:61], v[60:61], v[76:77] op_sel_hi:[1,1,0]
	v_and_b32_e32 v69, 0xffff0000, v42
	v_lshlrev_b32_e32 v42, 16, v43
	v_and_b32_e32 v43, 0xffff0000, v43
	v_mul_f32_e32 v84, v41, v41
	v_mov_b32_e32 v85, v77
	v_pk_fma_f32 v[102:103], v[64:65], v[64:65], v[82:83] op_sel_hi:[1,1,0]
	v_mov_b32_e32 v66, v80
	v_mov_b32_e32 v82, v100
	v_mul_f32_e32 v91, v69, v69
	v_mul_f32_e32 v93, v42, v42
	v_mul_f32_e32 v106, v43, v43
	v_mov_b32_e32 v68, v67
	v_pk_fma_f32 v[104:105], v[40:41], v[40:41], v[84:85] op_sel_hi:[1,1,0]
	v_pk_add_f32 v[80:81], v[80:81], v[100:101]
	v_pk_add_f32 v[62:63], v[62:63], v[62:63] op_sel:[0,1] op_sel_hi:[1,0]
	v_pk_mul_f32 v[66:67], v[66:67], v[82:83]
	v_lshlrev_b32_e32 v71, 16, v53
; __device__ __forceinline__ float bflo(unsigned w) { return __uint_as_float(w << 16); }
; __device__ __forceinline__ float bfhi(unsigned w) { return __uint_as_float(w & 0xffff0000u); }
; __device__ __forceinline__ float wave_sum(float v) {
; #pragma unroll
;     for (int o = 1; o < 64; o <<= 1) v += __shfl_xor(v, o);
;     return v;
; }
; __global__ void __launch_bounds__(NWAVES * 64, 2) fwd_kernel(Args a_param) {
;     ...
;             f32x4 x[8]; float ss = 0.f;
; #pragma unroll
;             for (int j = 0; j < 8; ++j) { const u32x2 w = hr[64 * j]; x[j] = (f32x4){bflo(w.x), bfhi(w.x), bflo(w.y), bfhi(w.y)}; ss += (x[j].x * x[j].x + x[j].y * x[j].y) + (x[j].z * x[j].z + x[j].w * x[j].w); }
;             const float rstd = 1.0f / sqrtf(wave_sum(ss) * (1.0f / DM) + EPS);
; #pragma unroll
;             for (int j = 0; j < 8; ++j) xr[64 * j] = (x[j] * rstd) * gq[j];
	v_lshlrev_b32_e32 v70, 16, v52
	v_and_b32_e32 v53, 0xffff0000, v53
	v_and_b32_e32 v52, 0xffff0000, v52
	v_mov_b32_e32 v103, v93
	v_mov_b32_e32 v105, v106
	v_mov_b32_e32 v63, v91
	v_mov_b32_e32 v81, v67
	v_pk_mul_f32 v[86:87], v[52:53], v[52:53]
	v_pk_add_f32 v[82:83], v[102:103], v[104:105]
	v_pk_add_f32 v[62:63], v[80:81], v[62:63]
	v_lshlrev_b32_e32 v73, 16, v55
	v_lshlrev_b32_e32 v72, 16, v54
	v_and_b32_e32 v55, 0xffff0000, v55
	v_and_b32_e32 v54, 0xffff0000, v54
	v_mov_b32_e32 v96, v70
	v_mov_b32_e32 v97, v52
	v_mov_b32_e32 v52, v71
	v_pk_fma_f32 v[70:71], v[70:71], v[70:71], v[86:87]
	v_pk_add_f32 v[62:63], v[62:63], v[82:83]
	v_lshlrev_b32_e32 v74, 16, v56
	v_and_b32_e32 v75, 0xffff0000, v56
	v_lshlrev_b32_e32 v56, 16, v57
	v_and_b32_e32 v57, 0xffff0000, v57
	v_pk_mul_f32 v[88:89], v[54:55], v[54:55]
	v_pk_add_f32 v[70:71], v[70:71], v[70:71] op_sel:[0,1] op_sel_hi:[1,0]
	v_pk_add_f32 v[62:63], v[62:63], v[62:63] op_sel:[0,1] op_sel_hi:[1,0]
	v_and_b32_e32 v79, 0xffff0000, v58
	v_lshlrev_b32_e32 v58, 16, v59
	v_and_b32_e32 v59, 0xffff0000, v59
	v_mul_f32_e32 v90, v75, v75
	v_mul_f32_e32 v92, v57, v57
	v_mov_b32_e32 v98, v72
	v_mov_b32_e32 v99, v54
	v_mov_b32_e32 v54, v73
	v_pk_fma_f32 v[72:73], v[72:73], v[72:73], v[88:89]
	v_mov_b32_e32 v84, v70
	v_mov_b32_e32 v76, v62
	v_mul_f32_e32 v107, v79, v79
	v_mul_f32_e32 v108, v58, v58
	v_mul_f32_e32 v109, v59, v59
	v_pk_fma_f32 v[86:87], v[74:75], v[74:75], v[90:91] op_sel_hi:[1,1,0]
	v_pk_fma_f32 v[88:89], v[56:57], v[56:57], v[92:93] op_sel_hi:[1,1,0]
	v_pk_add_f32 v[72:73], v[72:73], v[72:73] op_sel:[0,1] op_sel_hi:[1,0]
	v_pk_add_f32 v[62:63], v[62:63], v[70:71]
	v_pk_mul_f32 v[66:67], v[76:77], v[84:85]
	v_mov_b32_e32 v87, v108
	v_mov_b32_e32 v89, v109
	v_mov_b32_e32 v73, v107
	v_mov_b32_e32 v63, v67
	v_pk_add_f32 v[86:87], v[86:87], v[88:89]
	v_pk_add_f32 v[62:63], v[62:63], v[72:73]
	v_mov_b32_e32 v78, v77
	v_pk_add_f32 v[62:63], v[62:63], v[86:87]
	s_nop 0
	v_add_f32_e32 v62, v62, v63
	ds_bpermute_b32 v63, v44, v62
	s_waitcnt lgkmcnt(0)
	v_add_f32_e32 v62, v62, v63
	ds_bpermute_b32 v63, v45, v62
	s_waitcnt lgkmcnt(0)
	v_add_f32_e32 v62, v62, v63
	ds_bpermute_b32 v63, v46, v62
	s_waitcnt lgkmcnt(0)
	v_add_f32_e32 v62, v62, v63
	ds_bpermute_b32 v63, v47, v62
	s_waitcnt lgkmcnt(0)
	v_add_f32_e32 v62, v62, v63
	ds_bpermute_b32 v63, v48, v62
	s_waitcnt lgkmcnt(0)
	v_add_f32_e32 v62, v62, v63
	ds_bpermute_b32 v63, v49, v62
	s_waitcnt lgkmcnt(0)
	v_add_f32_e32 v62, v62, v63
	v_fmamk_f32 v62, v62, 0x3a000000, v50
	v_mul_f32_e32 v63, 0x4f800000, v62
	v_cmp_gt_f32_e32 vcc, s3, v62
	s_nop 1
	v_cndmask_b32_e32 v62, v62, v63, vcc
	v_sqrt_f32_e32 v63, v62
	s_nop 0
	v_add_u32_e32 v66, -1, v63
	v_add_u32_e32 v67, 1, v63
	v_fma_f32 v70, -v66, v63, v62
	v_fma_f32 v71, -v67, v63, v62
	v_cmp_ge_f32_e64 s[0:1], 0, v70
	s_nop 1
	v_cndmask_b32_e64 v63, v63, v66, s[0:1]
	v_cmp_lt_f32_e64 s[0:1], 0, v71
	s_nop 1
	v_cndmask_b32_e64 v63, v63, v67, s[0:1]
	v_mul_f32_e32 v66, 0x37800000, v63
	v_cndmask_b32_e32 v63, v63, v66, vcc
	v_cmp_class_f32_e32 vcc, v62, v51
	s_nop 1
	v_cndmask_b32_e32 v62, v63, v62, vcc
	v_div_scale_f32 v63, s[0:1], v62, v62, 1.0
	v_rcp_f32_e32 v67, v63
	v_div_scale_f32 v66, vcc, 1.0, v62, 1.0
	v_fma_f32 v70, -v63, v67, 1.0
	v_fmac_f32_e32 v67, v70, v67
	v_mul_f32_e32 v70, v66, v67
	v_fma_f32 v71, -v63, v70, v66
	v_fmac_f32_e32 v70, v71, v67
	v_fma_f32 v63, -v63, v70, v66
	v_div_fmas_f32 v63, v63, v67, v70
	v_div_fixup_f32 v62, v63, v62, 1.0
	v_pk_mul_f32 v[60:61], v[62:63], v[60:61] op_sel_hi:[0,1]
	v_pk_mul_f32 v[36:37], v[62:63], v[36:37] op_sel_hi:[0,1]
	v_pk_mul_f32 v[66:67], v[62:63], v[94:95] op_sel_hi:[0,1]
	v_pk_mul_f32 v[70:71], v[62:63], v[38:39] op_sel_hi:[0,1]
	v_pk_mul_f32 v[64:65], v[62:63], v[64:65] op_sel_hi:[0,1]
	v_pk_mul_f32 v[72:73], v[62:63], v[40:41] op_sel_hi:[0,1]
	v_pk_mul_f32 v[68:69], v[62:63], v[68:69] op_sel_hi:[0,1]
	v_pk_mul_f32 v[76:77], v[62:63], v[42:43] op_sel_hi:[0,1]
	v_pk_mul_f32 v[80:81], v[62:63], v[96:97] op_sel_hi:[0,1]
	v_pk_mul_f32 v[82:83], v[62:63], v[52:53] op_sel_hi:[0,1]
	v_pk_mul_f32 v[84:85], v[62:63], v[98:99] op_sel_hi:[0,1]
	v_pk_mul_f32 v[86:87], v[62:63], v[54:55] op_sel_hi:[0,1]
	v_pk_mul_f32 v[74:75], v[62:63], v[74:75] op_sel_hi:[0,1]
	v_pk_mul_f32 v[88:89], v[62:63], v[56:57] op_sel_hi:[0,1]
	v_pk_mul_f32 v[78:79], v[62:63], v[78:79] op_sel_hi:[0,1]
	v_pk_mul_f32 v[90:91], v[62:63], v[58:59] op_sel_hi:[0,1]
	v_pk_mul_f32 v[38:39], v[36:37], v[2:3]
	v_pk_mul_f32 v[36:37], v[60:61], v[0:1]
	v_pk_mul_f32 v[42:43], v[70:71], v[6:7]
	v_pk_mul_f32 v[40:41], v[66:67], v[4:5]
	v_pk_mul_f32 v[54:55], v[72:73], v[10:11]
	v_pk_mul_f32 v[52:53], v[64:65], v[8:9]
	v_pk_mul_f32 v[58:59], v[76:77], v[14:15]
	v_pk_mul_f32 v[56:57], v[68:69], v[12:13]
	v_pk_mul_f32 v[62:63], v[82:83], v[18:19]
	v_pk_mul_f32 v[60:61], v[80:81], v[16:17]
	v_pk_mul_f32 v[66:67], v[86:87], v[22:23]
	v_pk_mul_f32 v[64:65], v[84:85], v[20:21]
	v_pk_mul_f32 v[70:71], v[88:89], v[26:27]
	v_pk_mul_f32 v[68:69], v[74:75], v[24:25]
	v_pk_mul_f32 v[74:75], v[90:91], v[30:31]
	v_pk_mul_f32 v[72:73], v[78:79], v[28:29]
	global_store_dwordx4 v[32:33], v[36:39], off offset:-4096
	global_store_dwordx4 v[32:33], v[40:43], off offset:-3072
	global_store_dwordx4 v[32:33], v[52:55], off offset:-2048
	global_store_dwordx4 v[32:33], v[56:59], off offset:-1024
	global_store_dwordx4 v[32:33], v[60:63], off
	global_store_dwordx4 v[32:33], v[64:67], off offset:1024
	global_store_dwordx4 v[32:33], v[68:71], off offset:2048
	global_store_dwordx4 v[32:33], v[72:75], off offset:3072
	v_lshl_add_u64 v[32:33], v[32:33], 0, s[4:5]
	s_cbranch_scc1 .LBB0_1861
